# conv_fixup (down-proj prefix of latent row tiles): no store-ack wait between its three items
# speedup vs baseline: 1.0062x; 1.0062x over previous
.LBB0_573:
	s_or_b64 exec, exec, s[2:3]
	s_movk_i32 s2, 0x380
	v_cmp_gt_i32_e32 vcc, s2, v0
	s_and_saveexec_b64 s[2:3], vcc
	s_cbranch_execz .LBB0_576
	s_movk_i32 s40, 0xbf
	v_cmp_lt_i32_e64 s[40:41], s40, v0
	s_nop 0
	s_nop 0
	v_cndmask_b32_e64 v2, 0, 7, s[40:41]
	v_cmp_ne_u32_e32 vcc, s56, v2
	s_and_b64 exec, exec, vcc
	s_cbranch_execz .LBB0_576
	v_mov_b32_e32 v2, 0xfffffd40
	v_cndmask_b32_e64 v2, 0, v2, s[40:41]
	s_movk_i32 s57, 0x200
	v_add3_u32 v2, v0, v2, s57
	v_lshlrev_b32_e32 v58, 2, v2
	v_lshlrev_b32_e32 v2, 3, v2
	v_and_b32_e32 v3, 0x7c, v58
	s_movk_i32 s57, 0xff00
	v_and_or_b32 v2, v2, s57, v3
	v_mov_b32_e32 v3, s52
	v_mov_b32_e32 v4, s54
	v_cndmask_b32_e64 v3, v3, v4, s[40:41]
	v_mov_b32_e32 v4, s17
	v_mov_b32_e32 v5, s53
	s_waitcnt vmcnt(1)
	v_cndmask_b32_e64 v6, v4, v5, s[40:41]
	v_mov_b32_e32 v4, s13
	v_mov_b32_e32 v5, s19
	v_cndmask_b32_e64 v7, v4, v5, s[40:41]
	v_mov_b64_e32 v[4:5], s[50:51]
	s_movk_i32 s57, 0x5800
	v_ashrrev_i32_e32 v59, 31, v58
	v_mad_i64_i32 v[14:15], s[60:61], v7, s57, v[4:5]
	v_mad_i64_i32 v[6:7], s[60:61], v6, s57, v[4:5]
	v_mad_i64_i32 v[4:5], s[60:61], v3, s57, v[4:5]
	v_ashrrev_i32_e32 v3, 31, v2
	v_lshlrev_b64 v[46:47], 2, v[58:59]
	v_lshlrev_b64 v[16:17], 2, v[2:3]
	v_lshl_add_u64 v[22:23], s[44:45], 0, v[46:47]
	v_lshl_add_u64 v[30:31], v[4:5], 0, v[16:17]
	v_lshl_add_u64 v[8:9], s[34:35], 0, v[46:47]
	v_lshl_add_u64 v[38:39], v[6:7], 0, v[16:17]
	v_lshl_add_u64 v[18:19], s[48:49], 0, v[46:47]
	v_lshl_add_u64 v[42:43], v[14:15], 0, v[16:17]
	global_load_dwordx4 v[26:29], v[22:23], off
	v_lshl_add_u64 v[22:23], s[22:23], 0, v[46:47]
	v_lshl_add_u64 v[34:35], s[42:43], 0, v[46:47]
	global_load_dwordx4 v[2:5], v[30:31], off
	global_load_dwordx4 v[10:13], v[8:9], off
	global_load_dwordx4 v[14:17], v[42:43], off
	v_lshl_add_u64 v[44:45], s[38:39], 0, v[46:47]
	global_load_dwordx4 v[18:21], v[18:19], off
	v_lshl_add_u64 v[48:49], s[24:25], 0, v[46:47]
	global_load_dwordx4 v[6:9], v[38:39], off
	s_nop 0
	global_load_dwordx4 v[22:25], v[22:23], off
	s_nop 0
	global_load_dwordx4 v[30:33], v[30:31], off offset:512
	s_nop 0
	global_load_dwordx4 v[34:37], v[34:35], off
	s_nop 0
	global_load_dwordx4 v[38:41], v[38:39], off offset:512
	s_nop 0
	global_load_dwordx4 v[54:57], v[44:45], off
	s_nop 0
	global_load_dwordx4 v[42:45], v[42:43], off offset:512
	v_lshl_add_u64 v[46:47], s[36:37], 0, v[46:47]
	global_load_dwordx4 v[50:53], v[48:49], off
	s_waitcnt vmcnt(11)
	v_mov_b32_e32 v60, v2
	global_load_dwordx4 v[46:49], v[46:47], off
	s_waitcnt vmcnt(11)
	v_mov_b32_e32 v62, v10
	s_waitcnt vmcnt(9)
	v_mov_b32_e32 v66, v18
	s_waitcnt vmcnt(8)
	v_mov_b32_e32 v64, v6
	s_waitcnt vmcnt(6)
	v_mov_b32_e32 v61, v30
	s_waitcnt vmcnt(4)
	v_mov_b32_e32 v65, v38
	s_waitcnt vmcnt(3)
	v_mov_b32_e32 v67, v54
	v_mov_b32_e32 v63, v34
	v_pk_mul_f32 v[64:65], v[64:65], v[66:67]
	v_mov_b32_e32 v38, v7
	v_pk_fma_f32 v[60:61], v[60:61], v[62:63], v[64:65]
	v_mov_b32_e32 v62, v14
	s_waitcnt vmcnt(2)
	v_mov_b32_e32 v63, v42
	v_mov_b32_e32 v64, v26
	s_waitcnt vmcnt(1)
	v_mov_b32_e32 v65, v50
	v_pk_fma_f32 v[60:61], v[62:63], v[64:65], v[60:61]
	v_mov_b32_e32 v62, v22
	v_mov_b32_e32 v54, v19
	v_mov_b32_e32 v30, v3
	v_mov_b32_e32 v34, v11
	v_mov_b32_e32 v42, v15
	v_mov_b32_e32 v50, v27
	v_mov_b32_e32 v19, v56
	v_mov_b32_e32 v56, v21
	s_waitcnt vmcnt(0)
	v_mov_b32_e32 v63, v46
	v_pk_add_f32 v[60:61], v[62:63], v[60:61]
	v_mov_b32_e32 v46, v23
	v_mul_f32_e32 v2, 0xbfb8aa3b, v60
	v_exp_f32_e32 v2, v2
	s_nop 0
	v_add_f32_e32 v2, 1.0, v2
	v_div_scale_f32 v6, s[60:61], v2, v2, v60
	v_rcp_f32_e32 v10, v6
	s_nop 0
	v_fma_f32 v14, -v6, v10, 1.0
	v_fmac_f32_e32 v10, v14, v10
	v_div_scale_f32 v14, vcc, v60, v2, v60
	v_mul_f32_e32 v18, v14, v10
	v_fma_f32 v22, -v6, v18, v14
	v_fmac_f32_e32 v18, v22, v10
	v_fma_f32 v6, -v6, v18, v14
	v_div_fmas_f32 v6, v6, v10, v18
	v_div_fixup_f32 v2, v6, v2, v60
	v_mul_f32_e32 v6, v2, v61
	v_pk_mul_f32 v[2:3], v[38:39], v[54:55]
	s_nop 0
	v_pk_fma_f32 v[2:3], v[30:31], v[34:35], v[2:3]
	s_nop 0
	v_pk_fma_f32 v[2:3], v[42:43], v[50:51], v[2:3]
	s_nop 0
	v_pk_add_f32 v[2:3], v[46:47], v[2:3]
	s_nop 0
	v_mul_f32_e32 v7, 0xbfb8aa3b, v2
	v_exp_f32_e32 v7, v7
	s_nop 0
	v_add_f32_e32 v7, 1.0, v7
	v_div_scale_f32 v10, s[60:61], v7, v7, v2
	v_rcp_f32_e32 v11, v10
	s_nop 0
	v_fma_f32 v14, -v10, v11, 1.0
	v_fmac_f32_e32 v11, v14, v11
	v_div_scale_f32 v14, vcc, v2, v7, v2
	v_mul_f32_e32 v15, v14, v11
	v_fma_f32 v18, -v10, v15, v14
	v_fmac_f32_e32 v15, v18, v11
	v_fma_f32 v10, -v10, v15, v14
	v_div_fmas_f32 v10, v10, v11, v15
	v_div_fixup_f32 v2, v10, v7, v2
	v_mov_b32_e32 v14, v8
	v_mov_b32_e32 v15, v40
	v_mov_b32_e32 v18, v20
	v_mul_f32_e32 v7, v2, v3
	v_mov_b32_e32 v2, v4
	v_mov_b32_e32 v3, v32
	v_mov_b32_e32 v10, v12
	v_mov_b32_e32 v11, v36
	v_pk_mul_f32 v[14:15], v[14:15], v[18:19]
	v_mov_b32_e32 v40, v9
	v_pk_fma_f32 v[2:3], v[2:3], v[10:11], v[14:15]
	v_mov_b32_e32 v10, v16
	v_mov_b32_e32 v11, v44
	v_mov_b32_e32 v14, v28
	v_mov_b32_e32 v15, v52
	v_pk_fma_f32 v[2:3], v[10:11], v[14:15], v[2:3]
	v_mov_b32_e32 v10, v24
	v_mov_b32_e32 v11, v48
	v_pk_add_f32 v[2:3], v[10:11], v[2:3]
	v_mov_b32_e32 v32, v5
	v_mul_f32_e32 v4, 0xbfb8aa3b, v2
	v_exp_f32_e32 v4, v4
	v_mov_b32_e32 v36, v13
	v_mov_b32_e32 v44, v17
	v_mov_b32_e32 v52, v29
	v_add_f32_e32 v4, 1.0, v4
	v_div_scale_f32 v8, s[60:61], v4, v4, v2
	v_rcp_f32_e32 v10, v8
	v_mov_b32_e32 v48, v25
	v_fma_f32 v11, -v8, v10, 1.0
	v_fmac_f32_e32 v10, v11, v10
	v_div_scale_f32 v11, vcc, v2, v4, v2
	v_mul_f32_e32 v12, v11, v10
	v_fma_f32 v14, -v8, v12, v11
	v_fmac_f32_e32 v12, v14, v10
	v_fma_f32 v8, -v8, v12, v11
	v_div_fmas_f32 v8, v8, v10, v12
	v_div_fixup_f32 v2, v8, v4, v2
	v_mul_f32_e32 v4, v2, v3
	v_pk_mul_f32 v[2:3], v[40:41], v[56:57]
	s_nop 0
	v_pk_fma_f32 v[2:3], v[32:33], v[36:37], v[2:3]
	s_nop 0
	v_pk_fma_f32 v[2:3], v[44:45], v[52:53], v[2:3]
	s_nop 0
	v_pk_add_f32 v[2:3], v[48:49], v[2:3]
	s_nop 0
	v_mul_f32_e32 v5, 0xbfb8aa3b, v2
	v_exp_f32_e32 v5, v5
	s_nop 0
	v_add_f32_e32 v5, 1.0, v5
	v_div_scale_f32 v8, s[60:61], v5, v5, v2
	v_rcp_f32_e32 v9, v8
	s_nop 0
	v_fma_f32 v10, -v8, v9, 1.0
	v_fmac_f32_e32 v9, v10, v9
	v_div_scale_f32 v10, vcc, v2, v5, v2
	v_mul_f32_e32 v11, v10, v9
	v_fma_f32 v12, -v8, v11, v10
	v_fmac_f32_e32 v11, v12, v9
	v_fma_f32 v8, -v8, v11, v10
	v_div_fmas_f32 v8, v8, v9, v11
	v_div_fixup_f32 v2, v8, v5, v2
	v_mul_f32_e32 v3, v2, v3
	v_cvt_pk_bf16_f32 v2, v6, v7
	v_cvt_pk_bf16_f32 v3, v4, v3
	v_mov_b32_e32 v4, 0xff
	v_cndmask_b32_e64 v4, 0, v4, s[40:41]
	v_or_b32_e32 v6, s5, v4
	v_mov_b64_e32 v[4:5], s[6:7]
	s_movk_i32 s40, 0x1600
	v_mad_u64_u32 v[4:5], s[40:41], v6, s40, v[4:5]
	v_lshl_add_u64 v[4:5], v[58:59], 1, v[4:5]
	global_store_dwordx2 v[4:5], v[2:3], off
.LBB0_576:
	s_or_b64 exec, exec, s[2:3]
	s_movk_i32 s2, 0x180
	v_cmp_gt_i32_e32 vcc, s2, v0
	s_and_saveexec_b64 s[2:3], vcc
	s_mov_b64 s[60:61], 0x1600000
	s_cbranch_execz .LBB0_579
	s_movk_i32 s40, 0xfebf
	v_cmp_lt_i32_e64 s[40:41], s40, v0
	s_nop 0
	s_nop 0
	v_cndmask_b32_e64 v2, 0, 7, s[40:41]
	v_cmp_ne_u32_e32 vcc, s56, v2
	s_and_b64 exec, exec, vcc
	s_cbranch_execz .LBB0_579
	v_mov_b32_e32 v2, 0xfffffd40
	v_cndmask_b32_e64 v2, 0, v2, s[40:41]
	s_movk_i32 s56, 0x400
	v_add3_u32 v0, v0, v2, s56
	v_lshlrev_b32_e32 v58, 2, v0
	v_lshlrev_b32_e32 v0, 3, v0
	v_and_b32_e32 v2, 0x7c, v58
	s_movk_i32 s56, 0xff00
	v_and_or_b32 v2, v0, s56, v2
	v_mov_b32_e32 v0, s52
	v_mov_b32_e32 v3, s54
	v_cndmask_b32_e64 v0, v0, v3, s[40:41]
	v_mov_b32_e32 v3, s17
	v_mov_b32_e32 v4, s53
	v_cndmask_b32_e64 v3, v3, v4, s[40:41]
	v_mov_b32_e32 v4, s13
	v_mov_b32_e32 v5, s19
	s_waitcnt vmcnt(1)
	v_cndmask_b32_e64 v6, v4, v5, s[40:41]
	v_mov_b64_e32 v[4:5], s[50:51]
	s_movk_i32 s13, 0x5800
	v_ashrrev_i32_e32 v59, 31, v58
	v_mad_i64_i32 v[14:15], s[50:51], v6, s13, v[4:5]
	v_mad_i64_i32 v[6:7], s[50:51], v3, s13, v[4:5]
	v_ashrrev_i32_e32 v3, 31, v2
	v_lshlrev_b64 v[46:47], 2, v[58:59]
	v_mad_i64_i32 v[4:5], s[50:51], v0, s13, v[4:5]
	v_lshlrev_b64 v[16:17], 2, v[2:3]
	v_lshl_add_u64 v[22:23], s[44:45], 0, v[46:47]
	v_lshl_add_u64 v[30:31], v[4:5], 0, v[16:17]
	v_lshl_add_u64 v[8:9], s[34:35], 0, v[46:47]
	v_lshl_add_u64 v[38:39], v[6:7], 0, v[16:17]
	v_lshl_add_u64 v[18:19], s[48:49], 0, v[46:47]
	v_lshl_add_u64 v[42:43], v[14:15], 0, v[16:17]
	global_load_dwordx4 v[26:29], v[22:23], off
	v_lshl_add_u64 v[22:23], s[22:23], 0, v[46:47]
	v_lshl_add_u64 v[34:35], s[42:43], 0, v[46:47]
	global_load_dwordx4 v[2:5], v[30:31], off
	global_load_dwordx4 v[10:13], v[8:9], off
	global_load_dwordx4 v[14:17], v[42:43], off
	v_lshl_add_u64 v[44:45], s[38:39], 0, v[46:47]
	global_load_dwordx4 v[18:21], v[18:19], off
	v_lshl_add_u64 v[48:49], s[24:25], 0, v[46:47]
	global_load_dwordx4 v[6:9], v[38:39], off
	s_nop 0
	global_load_dwordx4 v[22:25], v[22:23], off
	s_nop 0
	global_load_dwordx4 v[30:33], v[30:31], off offset:512
	s_nop 0
	global_load_dwordx4 v[34:37], v[34:35], off
	s_nop 0
	global_load_dwordx4 v[38:41], v[38:39], off offset:512
	s_nop 0
	global_load_dwordx4 v[54:57], v[44:45], off
	s_nop 0
	global_load_dwordx4 v[42:45], v[42:43], off offset:512
	v_lshl_add_u64 v[46:47], s[36:37], 0, v[46:47]
	global_load_dwordx4 v[50:53], v[48:49], off
	s_waitcnt vmcnt(11)
	v_mov_b32_e32 v60, v2
	global_load_dwordx4 v[46:49], v[46:47], off
	s_waitcnt vmcnt(11)
	v_mov_b32_e32 v62, v10
	s_waitcnt vmcnt(9)
	v_mov_b32_e32 v66, v18
	s_waitcnt vmcnt(8)
	v_mov_b32_e32 v64, v6
	s_waitcnt vmcnt(6)
	v_mov_b32_e32 v61, v30
	s_waitcnt vmcnt(4)
	v_mov_b32_e32 v65, v38
	s_waitcnt vmcnt(3)
	v_mov_b32_e32 v67, v54
	v_mov_b32_e32 v63, v34
	v_pk_mul_f32 v[64:65], v[64:65], v[66:67]
	v_mov_b32_e32 v38, v7
	v_pk_fma_f32 v[60:61], v[60:61], v[62:63], v[64:65]
	v_mov_b32_e32 v62, v14
	s_waitcnt vmcnt(2)
	v_mov_b32_e32 v63, v42
	v_mov_b32_e32 v64, v26
	s_waitcnt vmcnt(1)
	v_mov_b32_e32 v65, v50
	v_pk_fma_f32 v[60:61], v[62:63], v[64:65], v[60:61]
	v_mov_b32_e32 v62, v22
	v_mov_b32_e32 v54, v19
	v_mov_b32_e32 v30, v3
	v_mov_b32_e32 v34, v11
	v_mov_b32_e32 v42, v15
	v_mov_b32_e32 v50, v27
	s_waitcnt vmcnt(0)
	v_mov_b32_e32 v63, v46
	v_pk_add_f32 v[60:61], v[62:63], v[60:61]
	v_mov_b32_e32 v46, v23
	v_mul_f32_e32 v0, 0xbfb8aa3b, v60
	v_exp_f32_e32 v0, v0
	s_nop 0
	v_add_f32_e32 v0, 1.0, v0
	v_div_scale_f32 v2, s[22:23], v0, v0, v60
	v_rcp_f32_e32 v6, v2
	s_nop 0
	v_fma_f32 v10, -v2, v6, 1.0
	v_fmac_f32_e32 v6, v10, v6
	v_div_scale_f32 v10, vcc, v60, v0, v60
	v_mul_f32_e32 v14, v10, v6
	v_fma_f32 v18, -v2, v14, v10
	v_fmac_f32_e32 v14, v18, v6
	v_fma_f32 v2, -v2, v14, v10
	v_div_fmas_f32 v2, v2, v6, v14
	v_div_fixup_f32 v0, v2, v0, v60
	v_pk_mul_f32 v[2:3], v[38:39], v[54:55]
	v_mul_f32_e32 v0, v0, v61
	v_pk_fma_f32 v[2:3], v[30:31], v[34:35], v[2:3]
	s_nop 0
	v_pk_fma_f32 v[2:3], v[42:43], v[50:51], v[2:3]
	s_nop 0
	v_pk_add_f32 v[2:3], v[46:47], v[2:3]
	s_nop 0
	v_mul_f32_e32 v6, 0xbfb8aa3b, v2
	v_exp_f32_e32 v6, v6
	s_nop 0
	v_add_f32_e32 v6, 1.0, v6
	v_div_scale_f32 v7, s[22:23], v6, v6, v2
	v_rcp_f32_e32 v10, v7
	s_nop 0
	v_fma_f32 v11, -v7, v10, 1.0
	v_fmac_f32_e32 v10, v11, v10
	v_div_scale_f32 v11, vcc, v2, v6, v2
	v_mul_f32_e32 v14, v11, v10
	v_fma_f32 v15, -v7, v14, v11
	v_fmac_f32_e32 v14, v15, v10
	v_fma_f32 v7, -v7, v14, v11
	v_div_fmas_f32 v7, v7, v10, v14
	v_div_fixup_f32 v2, v7, v6, v2
	v_mov_b32_e32 v10, v8
	v_mov_b32_e32 v11, v40
	v_mov_b32_e32 v14, v20
	v_mov_b32_e32 v15, v56
	v_mul_f32_e32 v18, v2, v3
	v_mov_b32_e32 v2, v4
	v_mov_b32_e32 v3, v32
	v_mov_b32_e32 v6, v12
	v_mov_b32_e32 v7, v36
	v_pk_mul_f32 v[10:11], v[10:11], v[14:15]
	v_mov_b32_e32 v40, v9
	v_pk_fma_f32 v[2:3], v[2:3], v[6:7], v[10:11]
	v_mov_b32_e32 v6, v16
	v_mov_b32_e32 v7, v44
	v_mov_b32_e32 v10, v28
	v_mov_b32_e32 v11, v52
	v_pk_fma_f32 v[2:3], v[6:7], v[10:11], v[2:3]
	v_mov_b32_e32 v6, v24
	v_mov_b32_e32 v7, v48
	v_pk_add_f32 v[2:3], v[6:7], v[2:3]
	v_mov_b32_e32 v56, v21
	v_mul_f32_e32 v4, 0xbfb8aa3b, v2
	v_exp_f32_e32 v4, v4
	v_mov_b32_e32 v32, v5
	v_mov_b32_e32 v36, v13
	v_mov_b32_e32 v44, v17
	v_add_f32_e32 v4, 1.0, v4
	v_div_scale_f32 v6, s[22:23], v4, v4, v2
	v_rcp_f32_e32 v7, v6
	v_mov_b32_e32 v52, v29
	v_mov_b32_e32 v48, v25
	v_fma_f32 v8, -v6, v7, 1.0
	v_fmac_f32_e32 v7, v8, v7
	v_div_scale_f32 v8, vcc, v2, v4, v2
	v_mul_f32_e32 v10, v8, v7
	v_fma_f32 v11, -v6, v10, v8
	v_fmac_f32_e32 v10, v11, v7
	v_fma_f32 v6, -v6, v10, v8
	v_div_fmas_f32 v6, v6, v7, v10
	v_div_fixup_f32 v2, v6, v4, v2
	v_mul_f32_e32 v4, v2, v3
	v_pk_mul_f32 v[2:3], v[40:41], v[56:57]
	s_nop 0
	v_pk_fma_f32 v[2:3], v[32:33], v[36:37], v[2:3]
	s_nop 0
	v_pk_fma_f32 v[2:3], v[44:45], v[52:53], v[2:3]
	s_nop 0
	v_pk_add_f32 v[2:3], v[48:49], v[2:3]
	s_nop 0
	v_mul_f32_e32 v5, 0xbfb8aa3b, v2
	v_exp_f32_e32 v5, v5
	s_nop 0
	v_add_f32_e32 v5, 1.0, v5
	v_div_scale_f32 v6, s[22:23], v5, v5, v2
	v_rcp_f32_e32 v7, v6
	s_nop 0
	v_fma_f32 v8, -v6, v7, 1.0
	v_fmac_f32_e32 v7, v8, v7
	v_div_scale_f32 v8, vcc, v2, v5, v2
	v_mul_f32_e32 v9, v8, v7
	v_fma_f32 v10, -v6, v9, v8
	v_fmac_f32_e32 v9, v10, v7
	v_fma_f32 v6, -v6, v9, v8
	v_div_fmas_f32 v6, v6, v7, v9
	v_div_fixup_f32 v2, v6, v5, v2
	v_mul_f32_e32 v3, v2, v3
	v_cvt_pk_bf16_f32 v2, v0, v18
	v_mov_b32_e32 v0, 0xff
	v_cndmask_b32_e64 v0, 0, v0, s[40:41]
	v_cvt_pk_bf16_f32 v3, v4, v3
	v_or_b32_e32 v0, s5, v0
	v_mov_b64_e32 v[4:5], s[6:7]
	s_movk_i32 s5, 0x1600
	v_mad_u64_u32 v[4:5], s[6:7], v0, s5, v[4:5]
	v_lshl_add_u64 v[4:5], v[58:59], 1, v[4:5]
	global_store_dwordx2 v[4:5], v[2:3], off
